# scan mLSTM: the wait before barrier B1 covers only the V tile DMAs (vmcnt 2), the next step's gate-scan loads issued after them are waited for at the next step's top
# baseline (speedup 1.0000x reference)
.LBB0_504:
	v_or_b32_e32 v100, v100, v99
	v_lshlrev_b32_e32 v160, 3, v130
	v_or_b32_e32 v72, v160, v98
	v_lshlrev_b32_e32 v132, 4, v100
	v_add_u32_e32 v101, s72, v72
	v_cvt_pk_bf16_f32 v66, v66, v67
	v_cvt_pk_bf16_f32 v67, v68, v69
	v_xor_b32_e32 v68, s73, v132
	v_add_u32_e32 v200, v101, v68
	v_xor_b32_e32 v68, s94, v132
	s_and_b64 vcc, exec, s[6:7]
	s_cbranch_vccnz .Lvw_all
	s_cmp_eq_u32 s41, 33
	s_cbranch_scc1 .Lvw_all
	s_waitcnt vmcnt(2) lgkmcnt(0)
	s_branch .Lvw_done
.Lvw_all:
	s_waitcnt vmcnt(0) lgkmcnt(0)
.Lvw_done:
	s_barrier
	ds_write_b64 v200, v[66:67]
	v_cvt_pk_bf16_f32 v66, v70, v71
	v_cvt_pk_bf16_f32 v67, v102, v73
	v_add_u32_e32 v201, v101, v68
	v_xor_b32_e32 v68, s95, v132
	v_cmp_gt_i32_e64 s[12:13], 64, v140
	ds_write_b64 v201, v[66:67]
	v_cvt_pk_bf16_f32 v66, v74, v75
	v_cvt_pk_bf16_f32 v67, v76, v77
	v_add_u32_e32 v202, v101, v68
	v_xor_b32_e32 v68, s78, v132
	s_and_b64 s[22:23], s[90:91], s[12:13]
	ds_write_b64 v202, v[66:67]
	v_cvt_pk_bf16_f32 v66, v78, v79
	v_cvt_pk_bf16_f32 v67, v80, v81
	v_add_u32_e32 v203, v101, v68
	ds_write_b64 v203, v[66:67]
	s_and_saveexec_b64 s[2:3], s[22:23]
	s_cbranch_execz .LBB0_506
	v_lshl_add_u32 v73, v140, 2, 0
	v_add_u32_e32 v68, 0x21000, v73
	ds_read2st64_b32 v[66:67], v68 offset1:2
	ds_read2st64_b32 v[68:69], v68 offset0:4 offset1:6
	s_waitcnt lgkmcnt(1)
	v_mov_b32_e32 v70, v66
	s_waitcnt lgkmcnt(0)
	v_mov_b32_e32 v71, v68
	v_mov_b32_e32 v68, v67
	v_pk_add_f32 v[66:67], v[70:71], v[68:69]
	v_add_u32_e32 v68, 0x20c00, v73
	v_add_f32_e32 v66, v66, v67
	v_add_u32_e32 v67, 0x20400, v73
	ds_read_b32 v67, v67
	ds_read_b32 v68, v68
	s_waitcnt lgkmcnt(0)
	v_fmac_f32_e32 v66, v67, v68
	v_add_u32_e32 v67, 0x20800, v73
	ds_read_b32 v67, v67
	s_waitcnt lgkmcnt(0)
	v_max_f32_e32 v67, v67, v67
	v_max_f32_e64 v66, |v66|, v67
	v_div_scale_f32 v67, s[8:9], v66, v66, 1.0
	v_rcp_f32_e32 v68, v67
	s_nop 0
	v_fma_f32 v69, -v67, v68, 1.0
	v_fmac_f32_e32 v68, v69, v68
	v_div_scale_f32 v69, vcc, 1.0, v66, 1.0
	v_mul_f32_e32 v70, v69, v68
	v_fma_f32 v71, -v67, v70, v69
	v_fmac_f32_e32 v70, v71, v68
	v_fma_f32 v67, -v67, v70, v69
	v_div_fmas_f32 v67, v67, v68, v70
	v_div_fixup_f32 v66, v67, v66, 1.0
	v_add_u32_e32 v67, 0x20a00, v73
	ds_write_b32 v67, v66
